# v26 + gr_pass (phase 5 start) rewritten: all 64 operand loads in flight (was ~16 dependent round trips), ssq loads up front
# speedup vs baseline: 1.0018x; 1.0018x over previous
; __device__ __forceinline__ void gr_pass(const bf16_t* hb, const bf16_t* WgrT, const float* ssq_in, float* gr) {
;     const int lane = threadIdx.x & 63, wid = threadIdx.x >> 6, fr = lane & 15, fq = lane >> 4;
;     for (int gidx = blockIdx.x * 8 + wid; gidx < M / 16; gidx += gridDim.x * 8) {
;         const int r0 = gidx * 16; f32x4 acc = (f32x4){0.f, 0.f, 0.f, 0.f};
;         const bf16_t* ap = hb + (size_t)(r0 + fr) * D + 8 * fq; const bf16_t* bp = WgrT + (size_t)fr * D + 8 * fq;
; #pragma unroll 8
;         for (int s = 0; s < 32; ++s) { const bf16x8 a = *(const bf16x8*)(ap + 32 * s), b = *(const bf16x8*)(bp + 32 * s); acc = __builtin_amdgcn_mfma_f32_16x16x32_bf16(a, b, acc, 0, 0, 0); }
.LBB0_1836:
	v_ashrrev_i32_e32 v11, 31, v10
	v_lshlrev_b64 v[0:1], 11, v[10:11]
	v_lshl_add_u64 v[14:15], v[8:9], 0, v[0:1]
	v_add_co_u32_e32 v18, vcc, 0x308dc00, v14
	v_addc_co_u32_e32 v19, vcc, 0, v15, vcc
	v_add_co_u32_e32 v20, vcc, 0x2c80000, v12
	v_addc_co_u32_e32 v21, vcc, 0, v13, vcc
	v_lshl_or_b32 v22, v16, 4, v17
	v_ashrrev_i32_e32 v23, 31, v22
	v_lshl_add_u64 v[24:25], v[22:23], 2, s[34:35]
	v_lshlrev_b64 v[26:27], 6, v[22:23]
	v_lshl_add_u64 v[26:27], v[6:7], 0, v[26:27]
	global_load_dword v28, v[24:25], off
	global_load_dword v29, v[24:25], off offset:4
	global_load_dword v30, v[24:25], off offset:8
	global_load_dword v31, v[24:25], off offset:12
	global_load_dwordx4 v[32:35], v[18:19], off
	global_load_dwordx4 v[160:163], v[20:21], off
	global_load_dwordx4 v[36:39], v[18:19], off offset:64
	global_load_dwordx4 v[164:167], v[20:21], off offset:64
	global_load_dwordx4 v[40:43], v[18:19], off offset:128
	global_load_dwordx4 v[168:171], v[20:21], off offset:128
	global_load_dwordx4 v[44:47], v[18:19], off offset:192
	global_load_dwordx4 v[172:175], v[20:21], off offset:192
	global_load_dwordx4 v[48:51], v[18:19], off offset:256
	global_load_dwordx4 v[176:179], v[20:21], off offset:256
	global_load_dwordx4 v[52:55], v[18:19], off offset:320
	global_load_dwordx4 v[180:183], v[20:21], off offset:320
	global_load_dwordx4 v[56:59], v[18:19], off offset:384
	global_load_dwordx4 v[184:187], v[20:21], off offset:384
	global_load_dwordx4 v[60:63], v[18:19], off offset:448
	global_load_dwordx4 v[188:191], v[20:21], off offset:448
	global_load_dwordx4 v[64:67], v[18:19], off offset:512
	global_load_dwordx4 v[192:195], v[20:21], off offset:512
	global_load_dwordx4 v[68:71], v[18:19], off offset:576
	global_load_dwordx4 v[196:199], v[20:21], off offset:576
	global_load_dwordx4 v[72:75], v[18:19], off offset:640
	global_load_dwordx4 v[200:203], v[20:21], off offset:640
	global_load_dwordx4 v[76:79], v[18:19], off offset:704
	global_load_dwordx4 v[204:207], v[20:21], off offset:704
	global_load_dwordx4 v[80:83], v[18:19], off offset:768
	global_load_dwordx4 v[212:215], v[20:21], off offset:768
	global_load_dwordx4 v[84:87], v[18:19], off offset:832
	global_load_dwordx4 v[216:219], v[20:21], off offset:832
	global_load_dwordx4 v[88:91], v[18:19], off offset:896
	global_load_dwordx4 v[220:223], v[20:21], off offset:896
	global_load_dwordx4 v[92:95], v[18:19], off offset:960
	global_load_dwordx4 v[224:227], v[20:21], off offset:960
	global_load_dwordx4 v[96:99], v[18:19], off offset:1024
	global_load_dwordx4 v[100:103], v[18:19], off offset:1088
	global_load_dwordx4 v[104:107], v[18:19], off offset:1152
	global_load_dwordx4 v[108:111], v[18:19], off offset:1216
	global_load_dwordx4 v[112:115], v[18:19], off offset:1280
	global_load_dwordx4 v[116:119], v[18:19], off offset:1344
	global_load_dwordx4 v[120:123], v[18:19], off offset:1408
	global_load_dwordx4 v[124:127], v[18:19], off offset:1472
	global_load_dwordx4 v[128:131], v[18:19], off offset:1536
	global_load_dwordx4 v[132:135], v[18:19], off offset:1600
	global_load_dwordx4 v[136:139], v[18:19], off offset:1664
	global_load_dwordx4 v[140:143], v[18:19], off offset:1728
	global_load_dwordx4 v[144:147], v[18:19], off offset:1792
	global_load_dwordx4 v[148:151], v[18:19], off offset:1856
	global_load_dwordx4 v[152:155], v[18:19], off offset:1920
	global_load_dwordx4 v[156:159], v[18:19], off offset:1984
	s_waitcnt vmcnt(46)
	v_mfma_f32_16x16x32_bf16 v[0:3], v[32:35], v[160:163], 0
	global_load_dwordx4 v[160:163], v[20:21], off offset:1024
	s_waitcnt vmcnt(45)
	v_mfma_f32_16x16x32_bf16 v[0:3], v[36:39], v[164:167], v[0:3]
	global_load_dwordx4 v[164:167], v[20:21], off offset:1088
	s_waitcnt vmcnt(44)
	v_mfma_f32_16x16x32_bf16 v[0:3], v[40:43], v[168:171], v[0:3]
	global_load_dwordx4 v[168:171], v[20:21], off offset:1152
	s_waitcnt vmcnt(43)
	v_mfma_f32_16x16x32_bf16 v[0:3], v[44:47], v[172:175], v[0:3]
	global_load_dwordx4 v[172:175], v[20:21], off offset:1216
	s_waitcnt vmcnt(42)
	v_mfma_f32_16x16x32_bf16 v[0:3], v[48:51], v[176:179], v[0:3]
	global_load_dwordx4 v[176:179], v[20:21], off offset:1280
	s_waitcnt vmcnt(41)
	v_mfma_f32_16x16x32_bf16 v[0:3], v[52:55], v[180:183], v[0:3]
	global_load_dwordx4 v[180:183], v[20:21], off offset:1344
	s_waitcnt vmcnt(40)
; __device__ __forceinline__ float rinv_of(float ssq) { return rsqrtf(ssq * (1.0f / 1024.0f) + EPS); }
; __device__ __forceinline__ void gr_pass(const bf16_t* hb, const bf16_t* WgrT, const float* ssq_in, float* gr) {
;     ...
;         for (int s = 0; s < 32; ++s) { const bf16x8 a = *(const bf16x8*)(ap + 32 * s), b = *(const bf16x8*)(bp + 32 * s); acc = __builtin_amdgcn_mfma_f32_16x16x32_bf16(a, b, acc, 0, 0, 0); }
; #pragma unroll
;         for (int j = 0; j < 4; ++j) { const int r = r0 + 4 * fq + j; gr[(size_t)r * 16 + fr] = acc[j] * rinv_of(ssq_in[r]); }
;     }
	v_mfma_f32_16x16x32_bf16 v[0:3], v[56:59], v[184:187], v[0:3]
	global_load_dwordx4 v[184:187], v[20:21], off offset:1408
	s_waitcnt vmcnt(39)
	v_mfma_f32_16x16x32_bf16 v[0:3], v[60:63], v[188:191], v[0:3]
	global_load_dwordx4 v[188:191], v[20:21], off offset:1472
	s_waitcnt vmcnt(38)
	v_mfma_f32_16x16x32_bf16 v[0:3], v[64:67], v[192:195], v[0:3]
	global_load_dwordx4 v[192:195], v[20:21], off offset:1536
	s_waitcnt vmcnt(37)
	v_mfma_f32_16x16x32_bf16 v[0:3], v[68:71], v[196:199], v[0:3]
	global_load_dwordx4 v[196:199], v[20:21], off offset:1600
	s_waitcnt vmcnt(36)
	v_mfma_f32_16x16x32_bf16 v[0:3], v[72:75], v[200:203], v[0:3]
	global_load_dwordx4 v[200:203], v[20:21], off offset:1664
	s_waitcnt vmcnt(35)
	v_mfma_f32_16x16x32_bf16 v[0:3], v[76:79], v[204:207], v[0:3]
	global_load_dwordx4 v[204:207], v[20:21], off offset:1728
	s_waitcnt vmcnt(34)
	v_mfma_f32_16x16x32_bf16 v[0:3], v[80:83], v[212:215], v[0:3]
	global_load_dwordx4 v[212:215], v[20:21], off offset:1792
	s_waitcnt vmcnt(33)
	v_mfma_f32_16x16x32_bf16 v[0:3], v[84:87], v[216:219], v[0:3]
	global_load_dwordx4 v[216:219], v[20:21], off offset:1856
	s_waitcnt vmcnt(32)
	v_mfma_f32_16x16x32_bf16 v[0:3], v[88:91], v[220:223], v[0:3]
	global_load_dwordx4 v[220:223], v[20:21], off offset:1920
	s_waitcnt vmcnt(31)
	v_mfma_f32_16x16x32_bf16 v[0:3], v[92:95], v[224:227], v[0:3]
	global_load_dwordx4 v[224:227], v[20:21], off offset:1984
	s_waitcnt vmcnt(15)
	v_mfma_f32_16x16x32_bf16 v[0:3], v[96:99], v[160:163], v[0:3]
	s_waitcnt vmcnt(14)
	v_mfma_f32_16x16x32_bf16 v[0:3], v[100:103], v[164:167], v[0:3]
	s_waitcnt vmcnt(13)
	v_mfma_f32_16x16x32_bf16 v[0:3], v[104:107], v[168:171], v[0:3]
	s_waitcnt vmcnt(12)
	v_mfma_f32_16x16x32_bf16 v[0:3], v[108:111], v[172:175], v[0:3]
	s_waitcnt vmcnt(11)
	v_mfma_f32_16x16x32_bf16 v[0:3], v[112:115], v[176:179], v[0:3]
	s_waitcnt vmcnt(10)
	v_mfma_f32_16x16x32_bf16 v[0:3], v[116:119], v[180:183], v[0:3]
	s_waitcnt vmcnt(9)
	v_mfma_f32_16x16x32_bf16 v[0:3], v[120:123], v[184:187], v[0:3]
	s_waitcnt vmcnt(8)
	v_mfma_f32_16x16x32_bf16 v[0:3], v[124:127], v[188:191], v[0:3]
	s_waitcnt vmcnt(7)
	v_mfma_f32_16x16x32_bf16 v[0:3], v[128:131], v[192:195], v[0:3]
	s_waitcnt vmcnt(6)
	v_mfma_f32_16x16x32_bf16 v[0:3], v[132:135], v[196:199], v[0:3]
	s_waitcnt vmcnt(5)
	v_mfma_f32_16x16x32_bf16 v[0:3], v[136:139], v[200:203], v[0:3]
	s_waitcnt vmcnt(4)
	v_mfma_f32_16x16x32_bf16 v[0:3], v[140:143], v[204:207], v[0:3]
	s_waitcnt vmcnt(3)
	v_mfma_f32_16x16x32_bf16 v[0:3], v[144:147], v[212:215], v[0:3]
	s_waitcnt vmcnt(2)
	v_mfma_f32_16x16x32_bf16 v[0:3], v[148:151], v[216:219], v[0:3]
	s_waitcnt vmcnt(1)
	v_mfma_f32_16x16x32_bf16 v[0:3], v[152:155], v[220:223], v[0:3]
	s_waitcnt vmcnt(0)
	v_mfma_f32_16x16x32_bf16 v[0:3], v[156:159], v[224:227], v[0:3]
	s_waitcnt vmcnt(0)
	v_fmamk_f32 v28, v28, 0x3a800000, v4
	v_fmamk_f32 v29, v29, 0x3a800000, v4
	v_fmamk_f32 v30, v30, 0x3a800000, v4
	v_fmamk_f32 v31, v31, 0x3a800000, v4
	v_mul_f32_e32 v160, 0x4b800000, v28
	v_cmp_gt_f32_e32 vcc, s13, v28
	s_nop 1
	v_cndmask_b32_e32 v28, v28, v160, vcc
	v_rsq_f32_e32 v28, v28
	s_nop 0
	v_mul_f32_e32 v160, 0x45800000, v28
	v_cndmask_b32_e32 v28, v28, v160, vcc
	v_mul_f32_e32 v161, 0x4b800000, v29
	v_cmp_gt_f32_e32 vcc, s13, v29
	s_nop 1
	v_cndmask_b32_e32 v29, v29, v161, vcc
	v_rsq_f32_e32 v29, v29
	s_nop 0
	v_mul_f32_e32 v161, 0x45800000, v29
	v_cndmask_b32_e32 v29, v29, v161, vcc
	v_mul_f32_e32 v162, 0x4b800000, v30
	v_cmp_gt_f32_e32 vcc, s13, v30
	s_nop 1
	v_cndmask_b32_e32 v30, v30, v162, vcc
	v_rsq_f32_e32 v30, v30
	s_nop 0
	v_mul_f32_e32 v162, 0x45800000, v30
	v_cndmask_b32_e32 v30, v30, v162, vcc
	v_mul_f32_e32 v163, 0x4b800000, v31
	v_cmp_gt_f32_e32 vcc, s13, v31
	s_nop 1
	v_cndmask_b32_e32 v31, v31, v163, vcc
	v_rsq_f32_e32 v31, v31
	s_nop 0
	v_mul_f32_e32 v163, 0x45800000, v31
	v_cndmask_b32_e32 v31, v31, v163, vcc
	s_nop 7
	v_mul_f32_e32 v0, v0, v28
	v_mul_f32_e32 v1, v1, v29
	v_mul_f32_e32 v2, v2, v30
	v_mul_f32_e32 v3, v3, v31
	global_store_dword v[26:27], v0, off
	global_store_dword v[26:27], v1, off offset:64
	global_store_dword v[26:27], v2, off offset:128
	global_store_dword v[26:27], v3, off offset:192
	v_add_u32_e32 v16, s3, v16
	v_add_u32_e32 v10, s12, v10
	v_cmp_lt_i32_e32 vcc, s14, v16
	s_or_b64 s[10:11], vcc, s[10:11]
	s_andn2_b64 exec, exec, s[10:11]
	s_cbranch_execnz .LBB0_1836
